# P0 silu staging fully unrolled: all 36 loads in flight before the first silu (on top of GEMV touch version)
# speedup vs baseline: 1.0040x; 1.0040x over previous
.LBB0_409:
	s_and_b64 vcc, exec, s[4:5]
	s_cbranch_vccz .LBB0_577
	s_movk_i32 s4, 0x4800
	v_cmp_gt_i32_e32 vcc, s4, v164
	s_and_saveexec_b64 s[4:5], vcc
	s_cbranch_execz .LBB0_413
	s_load_dwordx4 s[40:43], s[0:1], 0x48
	v_ashrrev_i32_e32 v165, 31, v164
	s_waitcnt vmcnt(0)
	v_lshlrev_b32_e32 v5, 2, v164
	s_mov_b32 s6, 0
	s_waitcnt lgkmcnt(0)
	global_load_dword v12, v5, s[40:41]
	v_add_u32_e32 v6, 0x2000, v5
	global_load_dword v13, v6, s[40:41]
	v_add_u32_e32 v7, 0x4000, v5
	global_load_dword v14, v7, s[40:41]
	v_add_u32_e32 v6, 0x6000, v5
	global_load_dword v15, v6, s[40:41]
	v_add_u32_e32 v7, 0x8000, v5
	global_load_dword v16, v7, s[40:41]
	v_add_u32_e32 v6, 0xa000, v5
	global_load_dword v17, v6, s[40:41]
	v_add_u32_e32 v7, 0xc000, v5
	global_load_dword v18, v7, s[40:41]
	v_add_u32_e32 v6, 0xe000, v5
	global_load_dword v19, v6, s[40:41]
	global_load_dword v20, v5, s[42:43]
	v_add_u32_e32 v6, 0x800, v5
	global_load_dword v21, v6, s[40:41]
	v_add_u32_e32 v7, 0x2800, v5
	global_load_dword v22, v7, s[40:41]
	v_add_u32_e32 v6, 0x4800, v5
	global_load_dword v23, v6, s[40:41]
	v_add_u32_e32 v7, 0x6800, v5
	global_load_dword v24, v7, s[40:41]
	v_add_u32_e32 v6, 0x8800, v5
	global_load_dword v25, v6, s[40:41]
	v_add_u32_e32 v7, 0xa800, v5
	global_load_dword v26, v7, s[40:41]
	v_add_u32_e32 v6, 0xc800, v5
	global_load_dword v27, v6, s[40:41]
	v_add_u32_e32 v7, 0xe800, v5
	global_load_dword v28, v7, s[40:41]
	v_add_u32_e32 v6, 0x800, v5
	global_load_dword v29, v6, s[42:43]
	v_add_u32_e32 v7, 0x1000, v5
	global_load_dword v30, v7, s[40:41]
	v_add_u32_e32 v6, 0x3000, v5
	global_load_dword v31, v6, s[40:41]
	v_add_u32_e32 v7, 0x5000, v5
	global_load_dword v32, v7, s[40:41]
	v_add_u32_e32 v6, 0x7000, v5
	global_load_dword v33, v6, s[40:41]
	v_add_u32_e32 v7, 0x9000, v5
	global_load_dword v34, v7, s[40:41]
	v_add_u32_e32 v6, 0xb000, v5
	global_load_dword v35, v6, s[40:41]
	v_add_u32_e32 v7, 0xd000, v5
	global_load_dword v36, v7, s[40:41]
	v_add_u32_e32 v6, 0xf000, v5
	global_load_dword v37, v6, s[40:41]
	v_add_u32_e32 v7, 0x1000, v5
	global_load_dword v38, v7, s[42:43]
	v_add_u32_e32 v6, 0x1800, v5
	global_load_dword v39, v6, s[40:41]
	v_add_u32_e32 v7, 0x3800, v5
	global_load_dword v40, v7, s[40:41]
	v_add_u32_e32 v6, 0x5800, v5
	global_load_dword v41, v6, s[40:41]
	v_add_u32_e32 v7, 0x7800, v5
	global_load_dword v42, v7, s[40:41]
	v_add_u32_e32 v6, 0x9800, v5
	global_load_dword v43, v6, s[40:41]
	v_add_u32_e32 v7, 0xb800, v5
	global_load_dword v44, v7, s[40:41]
	v_add_u32_e32 v6, 0xd800, v5
	global_load_dword v45, v6, s[40:41]
	v_add_u32_e32 v7, 0xf800, v5
	global_load_dword v46, v7, s[40:41]
	v_add_u32_e32 v6, 0x1800, v5
	global_load_dword v47, v6, s[42:43]
	v_add_u32_e32 v2, 0x8000, v5
	s_waitcnt vmcnt(35)
	v_mul_f32_e32 v6, 0xbfb8aa3b, v12
	v_exp_f32_e32 v6, v6
	s_nop 0
	v_add_f32_e32 v6, 1.0, v6
	v_div_scale_f32 v7, s[8:9], v6, v6, v12
	v_rcp_f32_e32 v8, v7
	v_div_scale_f32 v9, vcc, v12, v6, v12
	v_fma_f32 v10, -v7, v8, 1.0
	v_fmac_f32_e32 v8, v10, v8
	v_mul_f32_e32 v10, v9, v8
	v_fma_f32 v11, -v7, v10, v9
	v_fmac_f32_e32 v10, v11, v8
	v_fma_f32 v7, -v7, v10, v9
	v_div_fmas_f32 v7, v7, v8, v10
	v_div_fixup_f32 v0, v7, v6, v12
	ds_write_b32 v5, v0
	s_waitcnt vmcnt(34)
	v_mul_f32_e32 v6, 0xbfb8aa3b, v13
	v_exp_f32_e32 v6, v6
	s_nop 0
	v_add_f32_e32 v6, 1.0, v6
	v_div_scale_f32 v7, s[8:9], v6, v6, v13
	v_rcp_f32_e32 v8, v7
	v_div_scale_f32 v9, vcc, v13, v6, v13
	v_fma_f32 v10, -v7, v8, 1.0
	v_fmac_f32_e32 v8, v10, v8
	v_mul_f32_e32 v10, v9, v8
	v_fma_f32 v11, -v7, v10, v9
	v_fmac_f32_e32 v10, v11, v8
	v_fma_f32 v7, -v7, v10, v9
	v_div_fmas_f32 v7, v7, v8, v10
	v_div_fixup_f32 v0, v7, v6, v13
	ds_write_b32 v5, v0 offset:8192
	s_waitcnt vmcnt(33)
	v_mul_f32_e32 v6, 0xbfb8aa3b, v14
	v_exp_f32_e32 v6, v6
	s_nop 0
	v_add_f32_e32 v6, 1.0, v6
	v_div_scale_f32 v7, s[8:9], v6, v6, v14
	v_rcp_f32_e32 v8, v7
	v_div_scale_f32 v9, vcc, v14, v6, v14
	v_fma_f32 v10, -v7, v8, 1.0
	v_fmac_f32_e32 v8, v10, v8
	v_mul_f32_e32 v10, v9, v8
	v_fma_f32 v11, -v7, v10, v9
	v_fmac_f32_e32 v10, v11, v8
	v_fma_f32 v7, -v7, v10, v9
	v_div_fmas_f32 v7, v7, v8, v10
	v_div_fixup_f32 v0, v7, v6, v14
	ds_write_b32 v5, v0 offset:16384
	s_waitcnt vmcnt(32)
	v_mul_f32_e32 v6, 0xbfb8aa3b, v15
	v_exp_f32_e32 v6, v6
	s_nop 0
	v_add_f32_e32 v6, 1.0, v6
	v_div_scale_f32 v7, s[8:9], v6, v6, v15
	v_rcp_f32_e32 v8, v7
	v_div_scale_f32 v9, vcc, v15, v6, v15
	v_fma_f32 v10, -v7, v8, 1.0
	v_fmac_f32_e32 v8, v10, v8
	v_mul_f32_e32 v10, v9, v8
	v_fma_f32 v11, -v7, v10, v9
	v_fmac_f32_e32 v10, v11, v8
	v_fma_f32 v7, -v7, v10, v9
	v_div_fmas_f32 v7, v7, v8, v10
	v_div_fixup_f32 v0, v7, v6, v15
	ds_write_b32 v5, v0 offset:24576
	s_waitcnt vmcnt(31)
	v_mul_f32_e32 v6, 0xbfb8aa3b, v16
	v_exp_f32_e32 v6, v6
	s_nop 0
	v_add_f32_e32 v6, 1.0, v6
	v_div_scale_f32 v7, s[8:9], v6, v6, v16
	v_rcp_f32_e32 v8, v7
	v_div_scale_f32 v9, vcc, v16, v6, v16
	v_fma_f32 v10, -v7, v8, 1.0
	v_fmac_f32_e32 v8, v10, v8
	v_mul_f32_e32 v10, v9, v8
	v_fma_f32 v11, -v7, v10, v9
	v_fmac_f32_e32 v10, v11, v8
	v_fma_f32 v7, -v7, v10, v9
	v_div_fmas_f32 v7, v7, v8, v10
	v_div_fixup_f32 v0, v7, v6, v16
	ds_write_b32 v5, v0 offset:32768
	s_waitcnt vmcnt(30)
	v_mul_f32_e32 v6, 0xbfb8aa3b, v17
	v_exp_f32_e32 v6, v6
	s_nop 0
	v_add_f32_e32 v6, 1.0, v6
	v_div_scale_f32 v7, s[8:9], v6, v6, v17
	v_rcp_f32_e32 v8, v7
	v_div_scale_f32 v9, vcc, v17, v6, v17
	v_fma_f32 v10, -v7, v8, 1.0
	v_fmac_f32_e32 v8, v10, v8
	v_mul_f32_e32 v10, v9, v8
	v_fma_f32 v11, -v7, v10, v9
	v_fmac_f32_e32 v10, v11, v8
	v_fma_f32 v7, -v7, v10, v9
	v_div_fmas_f32 v7, v7, v8, v10
	v_div_fixup_f32 v0, v7, v6, v17
	ds_write_b32 v5, v0 offset:40960
	s_waitcnt vmcnt(29)
	v_mul_f32_e32 v6, 0xbfb8aa3b, v18
	v_exp_f32_e32 v6, v6
	s_nop 0
	v_add_f32_e32 v6, 1.0, v6
	v_div_scale_f32 v7, s[8:9], v6, v6, v18
	v_rcp_f32_e32 v8, v7
	v_div_scale_f32 v9, vcc, v18, v6, v18
	v_fma_f32 v10, -v7, v8, 1.0
	v_fmac_f32_e32 v8, v10, v8
	v_mul_f32_e32 v10, v9, v8
	v_fma_f32 v11, -v7, v10, v9
	v_fmac_f32_e32 v10, v11, v8
	v_fma_f32 v7, -v7, v10, v9
	v_div_fmas_f32 v7, v7, v8, v10
	v_div_fixup_f32 v0, v7, v6, v18
	ds_write_b32 v5, v0 offset:49152
	s_waitcnt vmcnt(28)
	v_mul_f32_e32 v6, 0xbfb8aa3b, v19
	v_exp_f32_e32 v6, v6
	s_nop 0
	v_add_f32_e32 v6, 1.0, v6
	v_div_scale_f32 v7, s[8:9], v6, v6, v19
	v_rcp_f32_e32 v8, v7
	v_div_scale_f32 v9, vcc, v19, v6, v19
	v_fma_f32 v10, -v7, v8, 1.0
	v_fmac_f32_e32 v8, v10, v8
	v_mul_f32_e32 v10, v9, v8
	v_fma_f32 v11, -v7, v10, v9
	v_fmac_f32_e32 v10, v11, v8
	v_fma_f32 v7, -v7, v10, v9
	v_div_fmas_f32 v7, v7, v8, v10
	v_div_fixup_f32 v0, v7, v6, v19
	ds_write_b32 v5, v0 offset:57344
	s_waitcnt vmcnt(27)
	v_mul_f32_e32 v6, 0xbfb8aa3b, v20
	v_exp_f32_e32 v6, v6
	s_nop 0
	v_add_f32_e32 v6, 1.0, v6
	v_div_scale_f32 v7, s[8:9], v6, v6, v20
	v_rcp_f32_e32 v8, v7
	v_div_scale_f32 v9, vcc, v20, v6, v20
	v_fma_f32 v10, -v7, v8, 1.0
	v_fmac_f32_e32 v8, v10, v8
	v_mul_f32_e32 v10, v9, v8
	v_fma_f32 v11, -v7, v10, v9
	v_fmac_f32_e32 v10, v11, v8
	v_fma_f32 v7, -v7, v10, v9
	v_div_fmas_f32 v7, v7, v8, v10
	v_div_fixup_f32 v0, v7, v6, v20
	ds_write_b32 v2, v0 offset:32768
	s_waitcnt vmcnt(26)
	v_mul_f32_e32 v6, 0xbfb8aa3b, v21
	v_exp_f32_e32 v6, v6
	s_nop 0
	v_add_f32_e32 v6, 1.0, v6
	v_div_scale_f32 v7, s[8:9], v6, v6, v21
	v_rcp_f32_e32 v8, v7
	v_div_scale_f32 v9, vcc, v21, v6, v21
	v_fma_f32 v10, -v7, v8, 1.0
	v_fmac_f32_e32 v8, v10, v8
	v_mul_f32_e32 v10, v9, v8
	v_fma_f32 v11, -v7, v10, v9
	v_fmac_f32_e32 v10, v11, v8
	v_fma_f32 v7, -v7, v10, v9
	v_div_fmas_f32 v7, v7, v8, v10
	v_div_fixup_f32 v0, v7, v6, v21
	ds_write_b32 v5, v0 offset:2048
	s_waitcnt vmcnt(25)
	v_mul_f32_e32 v6, 0xbfb8aa3b, v22
	v_exp_f32_e32 v6, v6
	s_nop 0
	v_add_f32_e32 v6, 1.0, v6
	v_div_scale_f32 v7, s[8:9], v6, v6, v22
	v_rcp_f32_e32 v8, v7
	v_div_scale_f32 v9, vcc, v22, v6, v22
	v_fma_f32 v10, -v7, v8, 1.0
	v_fmac_f32_e32 v8, v10, v8
	v_mul_f32_e32 v10, v9, v8
	v_fma_f32 v11, -v7, v10, v9
	v_fmac_f32_e32 v10, v11, v8
	v_fma_f32 v7, -v7, v10, v9
	v_div_fmas_f32 v7, v7, v8, v10
	v_div_fixup_f32 v0, v7, v6, v22
	ds_write_b32 v5, v0 offset:10240
	s_waitcnt vmcnt(24)
	v_mul_f32_e32 v6, 0xbfb8aa3b, v23
	v_exp_f32_e32 v6, v6
	s_nop 0
	v_add_f32_e32 v6, 1.0, v6
	v_div_scale_f32 v7, s[8:9], v6, v6, v23
	v_rcp_f32_e32 v8, v7
	v_div_scale_f32 v9, vcc, v23, v6, v23
	v_fma_f32 v10, -v7, v8, 1.0
	v_fmac_f32_e32 v8, v10, v8
	v_mul_f32_e32 v10, v9, v8
	v_fma_f32 v11, -v7, v10, v9
	v_fmac_f32_e32 v10, v11, v8
	v_fma_f32 v7, -v7, v10, v9
	v_div_fmas_f32 v7, v7, v8, v10
	v_div_fixup_f32 v0, v7, v6, v23
	ds_write_b32 v5, v0 offset:18432
	s_waitcnt vmcnt(23)
	v_mul_f32_e32 v6, 0xbfb8aa3b, v24
	v_exp_f32_e32 v6, v6
	s_nop 0
	v_add_f32_e32 v6, 1.0, v6
	v_div_scale_f32 v7, s[8:9], v6, v6, v24
	v_rcp_f32_e32 v8, v7
	v_div_scale_f32 v9, vcc, v24, v6, v24
	v_fma_f32 v10, -v7, v8, 1.0
	v_fmac_f32_e32 v8, v10, v8
	v_mul_f32_e32 v10, v9, v8
	v_fma_f32 v11, -v7, v10, v9
	v_fmac_f32_e32 v10, v11, v8
	v_fma_f32 v7, -v7, v10, v9
	v_div_fmas_f32 v7, v7, v8, v10
	v_div_fixup_f32 v0, v7, v6, v24
	ds_write_b32 v5, v0 offset:26624
	s_waitcnt vmcnt(22)
	v_mul_f32_e32 v6, 0xbfb8aa3b, v25
	v_exp_f32_e32 v6, v6
	s_nop 0
	v_add_f32_e32 v6, 1.0, v6
	v_div_scale_f32 v7, s[8:9], v6, v6, v25
	v_rcp_f32_e32 v8, v7
	v_div_scale_f32 v9, vcc, v25, v6, v25
	v_fma_f32 v10, -v7, v8, 1.0
	v_fmac_f32_e32 v8, v10, v8
	v_mul_f32_e32 v10, v9, v8
	v_fma_f32 v11, -v7, v10, v9
	v_fmac_f32_e32 v10, v11, v8
	v_fma_f32 v7, -v7, v10, v9
	v_div_fmas_f32 v7, v7, v8, v10
	v_div_fixup_f32 v0, v7, v6, v25
	ds_write_b32 v5, v0 offset:34816
	s_waitcnt vmcnt(21)
	v_mul_f32_e32 v6, 0xbfb8aa3b, v26
	v_exp_f32_e32 v6, v6
	s_nop 0
	v_add_f32_e32 v6, 1.0, v6
	v_div_scale_f32 v7, s[8:9], v6, v6, v26
	v_rcp_f32_e32 v8, v7
	v_div_scale_f32 v9, vcc, v26, v6, v26
	v_fma_f32 v10, -v7, v8, 1.0
	v_fmac_f32_e32 v8, v10, v8
	v_mul_f32_e32 v10, v9, v8
	v_fma_f32 v11, -v7, v10, v9
	v_fmac_f32_e32 v10, v11, v8
	v_fma_f32 v7, -v7, v10, v9
	v_div_fmas_f32 v7, v7, v8, v10
	v_div_fixup_f32 v0, v7, v6, v26
	ds_write_b32 v5, v0 offset:43008
	s_waitcnt vmcnt(20)
	v_mul_f32_e32 v6, 0xbfb8aa3b, v27
	v_exp_f32_e32 v6, v6
	s_nop 0
	v_add_f32_e32 v6, 1.0, v6
	v_div_scale_f32 v7, s[8:9], v6, v6, v27
	v_rcp_f32_e32 v8, v7
	v_div_scale_f32 v9, vcc, v27, v6, v27
	v_fma_f32 v10, -v7, v8, 1.0
	v_fmac_f32_e32 v8, v10, v8
	v_mul_f32_e32 v10, v9, v8
	v_fma_f32 v11, -v7, v10, v9
	v_fmac_f32_e32 v10, v11, v8
	v_fma_f32 v7, -v7, v10, v9
	v_div_fmas_f32 v7, v7, v8, v10
	v_div_fixup_f32 v0, v7, v6, v27
	ds_write_b32 v5, v0 offset:51200
	s_waitcnt vmcnt(19)
	v_mul_f32_e32 v6, 0xbfb8aa3b, v28
	v_exp_f32_e32 v6, v6
	s_nop 0
	v_add_f32_e32 v6, 1.0, v6
	v_div_scale_f32 v7, s[8:9], v6, v6, v28
	v_rcp_f32_e32 v8, v7
	v_div_scale_f32 v9, vcc, v28, v6, v28
	v_fma_f32 v10, -v7, v8, 1.0
	v_fmac_f32_e32 v8, v10, v8
	v_mul_f32_e32 v10, v9, v8
	v_fma_f32 v11, -v7, v10, v9
	v_fmac_f32_e32 v10, v11, v8
	v_fma_f32 v7, -v7, v10, v9
	v_div_fmas_f32 v7, v7, v8, v10
	v_div_fixup_f32 v0, v7, v6, v28
	ds_write_b32 v5, v0 offset:59392
	s_waitcnt vmcnt(18)
	v_mul_f32_e32 v6, 0xbfb8aa3b, v29
	v_exp_f32_e32 v6, v6
	s_nop 0
	v_add_f32_e32 v6, 1.0, v6
	v_div_scale_f32 v7, s[8:9], v6, v6, v29
	v_rcp_f32_e32 v8, v7
	v_div_scale_f32 v9, vcc, v29, v6, v29
	v_fma_f32 v10, -v7, v8, 1.0
	v_fmac_f32_e32 v8, v10, v8
	v_mul_f32_e32 v10, v9, v8
	v_fma_f32 v11, -v7, v10, v9
	v_fmac_f32_e32 v10, v11, v8
	v_fma_f32 v7, -v7, v10, v9
	v_div_fmas_f32 v7, v7, v8, v10
	v_div_fixup_f32 v0, v7, v6, v29
	ds_write_b32 v2, v0 offset:34816
	s_waitcnt vmcnt(17)
	v_mul_f32_e32 v6, 0xbfb8aa3b, v30
	v_exp_f32_e32 v6, v6
	s_nop 0
	v_add_f32_e32 v6, 1.0, v6
	v_div_scale_f32 v7, s[8:9], v6, v6, v30
	v_rcp_f32_e32 v8, v7
	v_div_scale_f32 v9, vcc, v30, v6, v30
	v_fma_f32 v10, -v7, v8, 1.0
	v_fmac_f32_e32 v8, v10, v8
	v_mul_f32_e32 v10, v9, v8
	v_fma_f32 v11, -v7, v10, v9
	v_fmac_f32_e32 v10, v11, v8
	v_fma_f32 v7, -v7, v10, v9
	v_div_fmas_f32 v7, v7, v8, v10
	v_div_fixup_f32 v0, v7, v6, v30
	ds_write_b32 v5, v0 offset:4096
	s_waitcnt vmcnt(16)
	v_mul_f32_e32 v6, 0xbfb8aa3b, v31
	v_exp_f32_e32 v6, v6
	s_nop 0
	v_add_f32_e32 v6, 1.0, v6
	v_div_scale_f32 v7, s[8:9], v6, v6, v31
	v_rcp_f32_e32 v8, v7
	v_div_scale_f32 v9, vcc, v31, v6, v31
	v_fma_f32 v10, -v7, v8, 1.0
	v_fmac_f32_e32 v8, v10, v8
	v_mul_f32_e32 v10, v9, v8
	v_fma_f32 v11, -v7, v10, v9
	v_fmac_f32_e32 v10, v11, v8
	v_fma_f32 v7, -v7, v10, v9
	v_div_fmas_f32 v7, v7, v8, v10
	v_div_fixup_f32 v0, v7, v6, v31
	ds_write_b32 v5, v0 offset:12288
	s_waitcnt vmcnt(15)
	v_mul_f32_e32 v6, 0xbfb8aa3b, v32
	v_exp_f32_e32 v6, v6
	s_nop 0
	v_add_f32_e32 v6, 1.0, v6
	v_div_scale_f32 v7, s[8:9], v6, v6, v32
	v_rcp_f32_e32 v8, v7
	v_div_scale_f32 v9, vcc, v32, v6, v32
	v_fma_f32 v10, -v7, v8, 1.0
	v_fmac_f32_e32 v8, v10, v8
	v_mul_f32_e32 v10, v9, v8
	v_fma_f32 v11, -v7, v10, v9
	v_fmac_f32_e32 v10, v11, v8
	v_fma_f32 v7, -v7, v10, v9
	v_div_fmas_f32 v7, v7, v8, v10
	v_div_fixup_f32 v0, v7, v6, v32
	ds_write_b32 v5, v0 offset:20480
	s_waitcnt vmcnt(14)
	v_mul_f32_e32 v6, 0xbfb8aa3b, v33
	v_exp_f32_e32 v6, v6
	s_nop 0
	v_add_f32_e32 v6, 1.0, v6
	v_div_scale_f32 v7, s[8:9], v6, v6, v33
	v_rcp_f32_e32 v8, v7
	v_div_scale_f32 v9, vcc, v33, v6, v33
	v_fma_f32 v10, -v7, v8, 1.0
	v_fmac_f32_e32 v8, v10, v8
	v_mul_f32_e32 v10, v9, v8
	v_fma_f32 v11, -v7, v10, v9
	v_fmac_f32_e32 v10, v11, v8
	v_fma_f32 v7, -v7, v10, v9
	v_div_fmas_f32 v7, v7, v8, v10
	v_div_fixup_f32 v0, v7, v6, v33
	ds_write_b32 v5, v0 offset:28672
	s_waitcnt vmcnt(13)
	v_mul_f32_e32 v6, 0xbfb8aa3b, v34
	v_exp_f32_e32 v6, v6
	s_nop 0
	v_add_f32_e32 v6, 1.0, v6
	v_div_scale_f32 v7, s[8:9], v6, v6, v34
	v_rcp_f32_e32 v8, v7
	v_div_scale_f32 v9, vcc, v34, v6, v34
	v_fma_f32 v10, -v7, v8, 1.0
	v_fmac_f32_e32 v8, v10, v8
	v_mul_f32_e32 v10, v9, v8
	v_fma_f32 v11, -v7, v10, v9
	v_fmac_f32_e32 v10, v11, v8
	v_fma_f32 v7, -v7, v10, v9
	v_div_fmas_f32 v7, v7, v8, v10
	v_div_fixup_f32 v0, v7, v6, v34
	ds_write_b32 v5, v0 offset:36864
	s_waitcnt vmcnt(12)
	v_mul_f32_e32 v6, 0xbfb8aa3b, v35
	v_exp_f32_e32 v6, v6
	s_nop 0
	v_add_f32_e32 v6, 1.0, v6
	v_div_scale_f32 v7, s[8:9], v6, v6, v35
	v_rcp_f32_e32 v8, v7
	v_div_scale_f32 v9, vcc, v35, v6, v35
	v_fma_f32 v10, -v7, v8, 1.0
	v_fmac_f32_e32 v8, v10, v8
	v_mul_f32_e32 v10, v9, v8
	v_fma_f32 v11, -v7, v10, v9
	v_fmac_f32_e32 v10, v11, v8
	v_fma_f32 v7, -v7, v10, v9
	v_div_fmas_f32 v7, v7, v8, v10
	v_div_fixup_f32 v0, v7, v6, v35
	ds_write_b32 v5, v0 offset:45056
	s_waitcnt vmcnt(11)
	v_mul_f32_e32 v6, 0xbfb8aa3b, v36
	v_exp_f32_e32 v6, v6
	s_nop 0
	v_add_f32_e32 v6, 1.0, v6
	v_div_scale_f32 v7, s[8:9], v6, v6, v36
	v_rcp_f32_e32 v8, v7
	v_div_scale_f32 v9, vcc, v36, v6, v36
	v_fma_f32 v10, -v7, v8, 1.0
	v_fmac_f32_e32 v8, v10, v8
	v_mul_f32_e32 v10, v9, v8
	v_fma_f32 v11, -v7, v10, v9
	v_fmac_f32_e32 v10, v11, v8
	v_fma_f32 v7, -v7, v10, v9
	v_div_fmas_f32 v7, v7, v8, v10
	v_div_fixup_f32 v0, v7, v6, v36
	ds_write_b32 v5, v0 offset:53248
	s_waitcnt vmcnt(10)
	v_mul_f32_e32 v6, 0xbfb8aa3b, v37
	v_exp_f32_e32 v6, v6
	s_nop 0
	v_add_f32_e32 v6, 1.0, v6
	v_div_scale_f32 v7, s[8:9], v6, v6, v37
	v_rcp_f32_e32 v8, v7
	v_div_scale_f32 v9, vcc, v37, v6, v37
	v_fma_f32 v10, -v7, v8, 1.0
	v_fmac_f32_e32 v8, v10, v8
	v_mul_f32_e32 v10, v9, v8
	v_fma_f32 v11, -v7, v10, v9
	v_fmac_f32_e32 v10, v11, v8
	v_fma_f32 v7, -v7, v10, v9
	v_div_fmas_f32 v7, v7, v8, v10
	v_div_fixup_f32 v0, v7, v6, v37
	ds_write_b32 v5, v0 offset:61440
	s_waitcnt vmcnt(9)
	v_mul_f32_e32 v6, 0xbfb8aa3b, v38
	v_exp_f32_e32 v6, v6
	s_nop 0
	v_add_f32_e32 v6, 1.0, v6
	v_div_scale_f32 v7, s[8:9], v6, v6, v38
	v_rcp_f32_e32 v8, v7
	v_div_scale_f32 v9, vcc, v38, v6, v38
	v_fma_f32 v10, -v7, v8, 1.0
	v_fmac_f32_e32 v8, v10, v8
	v_mul_f32_e32 v10, v9, v8
	v_fma_f32 v11, -v7, v10, v9
	v_fmac_f32_e32 v10, v11, v8
	v_fma_f32 v7, -v7, v10, v9
	v_div_fmas_f32 v7, v7, v8, v10
	v_div_fixup_f32 v0, v7, v6, v38
	ds_write_b32 v2, v0 offset:36864
	s_waitcnt vmcnt(8)
	v_mul_f32_e32 v6, 0xbfb8aa3b, v39
	v_exp_f32_e32 v6, v6
	s_nop 0
	v_add_f32_e32 v6, 1.0, v6
	v_div_scale_f32 v7, s[8:9], v6, v6, v39
	v_rcp_f32_e32 v8, v7
	v_div_scale_f32 v9, vcc, v39, v6, v39
	v_fma_f32 v10, -v7, v8, 1.0
	v_fmac_f32_e32 v8, v10, v8
	v_mul_f32_e32 v10, v9, v8
	v_fma_f32 v11, -v7, v10, v9
	v_fmac_f32_e32 v10, v11, v8
	v_fma_f32 v7, -v7, v10, v9
	v_div_fmas_f32 v7, v7, v8, v10
	v_div_fixup_f32 v0, v7, v6, v39
	ds_write_b32 v5, v0 offset:6144
	s_waitcnt vmcnt(7)
	v_mul_f32_e32 v6, 0xbfb8aa3b, v40
	v_exp_f32_e32 v6, v6
	s_nop 0
	v_add_f32_e32 v6, 1.0, v6
	v_div_scale_f32 v7, s[8:9], v6, v6, v40
	v_rcp_f32_e32 v8, v7
	v_div_scale_f32 v9, vcc, v40, v6, v40
	v_fma_f32 v10, -v7, v8, 1.0
	v_fmac_f32_e32 v8, v10, v8
	v_mul_f32_e32 v10, v9, v8
	v_fma_f32 v11, -v7, v10, v9
	v_fmac_f32_e32 v10, v11, v8
	v_fma_f32 v7, -v7, v10, v9
	v_div_fmas_f32 v7, v7, v8, v10
	v_div_fixup_f32 v0, v7, v6, v40
	ds_write_b32 v5, v0 offset:14336
	s_waitcnt vmcnt(6)
	v_mul_f32_e32 v6, 0xbfb8aa3b, v41
	v_exp_f32_e32 v6, v6
	s_nop 0
	v_add_f32_e32 v6, 1.0, v6
	v_div_scale_f32 v7, s[8:9], v6, v6, v41
	v_rcp_f32_e32 v8, v7
	v_div_scale_f32 v9, vcc, v41, v6, v41
	v_fma_f32 v10, -v7, v8, 1.0
	v_fmac_f32_e32 v8, v10, v8
	v_mul_f32_e32 v10, v9, v8
	v_fma_f32 v11, -v7, v10, v9
	v_fmac_f32_e32 v10, v11, v8
	v_fma_f32 v7, -v7, v10, v9
	v_div_fmas_f32 v7, v7, v8, v10
	v_div_fixup_f32 v0, v7, v6, v41
	ds_write_b32 v5, v0 offset:22528
	s_waitcnt vmcnt(5)
	v_mul_f32_e32 v6, 0xbfb8aa3b, v42
	v_exp_f32_e32 v6, v6
	s_nop 0
	v_add_f32_e32 v6, 1.0, v6
	v_div_scale_f32 v7, s[8:9], v6, v6, v42
	v_rcp_f32_e32 v8, v7
	v_div_scale_f32 v9, vcc, v42, v6, v42
	v_fma_f32 v10, -v7, v8, 1.0
	v_fmac_f32_e32 v8, v10, v8
	v_mul_f32_e32 v10, v9, v8
	v_fma_f32 v11, -v7, v10, v9
	v_fmac_f32_e32 v10, v11, v8
	v_fma_f32 v7, -v7, v10, v9
	v_div_fmas_f32 v7, v7, v8, v10
	v_div_fixup_f32 v0, v7, v6, v42
	ds_write_b32 v5, v0 offset:30720
	s_waitcnt vmcnt(4)
	v_mul_f32_e32 v6, 0xbfb8aa3b, v43
	v_exp_f32_e32 v6, v6
	s_nop 0
	v_add_f32_e32 v6, 1.0, v6
	v_div_scale_f32 v7, s[8:9], v6, v6, v43
	v_rcp_f32_e32 v8, v7
	v_div_scale_f32 v9, vcc, v43, v6, v43
	v_fma_f32 v10, -v7, v8, 1.0
	v_fmac_f32_e32 v8, v10, v8
	v_mul_f32_e32 v10, v9, v8
	v_fma_f32 v11, -v7, v10, v9
	v_fmac_f32_e32 v10, v11, v8
	v_fma_f32 v7, -v7, v10, v9
	v_div_fmas_f32 v7, v7, v8, v10
	v_div_fixup_f32 v0, v7, v6, v43
	ds_write_b32 v5, v0 offset:38912
	s_waitcnt vmcnt(3)
	v_mul_f32_e32 v6, 0xbfb8aa3b, v44
	v_exp_f32_e32 v6, v6
	s_nop 0
	v_add_f32_e32 v6, 1.0, v6
	v_div_scale_f32 v7, s[8:9], v6, v6, v44
	v_rcp_f32_e32 v8, v7
	v_div_scale_f32 v9, vcc, v44, v6, v44
	v_fma_f32 v10, -v7, v8, 1.0
	v_fmac_f32_e32 v8, v10, v8
	v_mul_f32_e32 v10, v9, v8
	v_fma_f32 v11, -v7, v10, v9
	v_fmac_f32_e32 v10, v11, v8
	v_fma_f32 v7, -v7, v10, v9
	v_div_fmas_f32 v7, v7, v8, v10
	v_div_fixup_f32 v0, v7, v6, v44
	ds_write_b32 v5, v0 offset:47104
	s_waitcnt vmcnt(2)
	v_mul_f32_e32 v6, 0xbfb8aa3b, v45
	v_exp_f32_e32 v6, v6
	s_nop 0
	v_add_f32_e32 v6, 1.0, v6
	v_div_scale_f32 v7, s[8:9], v6, v6, v45
	v_rcp_f32_e32 v8, v7
	v_div_scale_f32 v9, vcc, v45, v6, v45
	v_fma_f32 v10, -v7, v8, 1.0
	v_fmac_f32_e32 v8, v10, v8
	v_mul_f32_e32 v10, v9, v8
	v_fma_f32 v11, -v7, v10, v9
	v_fmac_f32_e32 v10, v11, v8
	v_fma_f32 v7, -v7, v10, v9
	v_div_fmas_f32 v7, v7, v8, v10
	v_div_fixup_f32 v0, v7, v6, v45
	ds_write_b32 v5, v0 offset:55296
	s_waitcnt vmcnt(1)
	v_mul_f32_e32 v6, 0xbfb8aa3b, v46
	v_exp_f32_e32 v6, v6
	s_nop 0
	v_add_f32_e32 v6, 1.0, v6
	v_div_scale_f32 v7, s[8:9], v6, v6, v46
	v_rcp_f32_e32 v8, v7
	v_div_scale_f32 v9, vcc, v46, v6, v46
	v_fma_f32 v10, -v7, v8, 1.0
	v_fmac_f32_e32 v8, v10, v8
	v_mul_f32_e32 v10, v9, v8
	v_fma_f32 v11, -v7, v10, v9
	v_fmac_f32_e32 v10, v11, v8
	v_fma_f32 v7, -v7, v10, v9
	v_div_fmas_f32 v7, v7, v8, v10
	v_div_fixup_f32 v0, v7, v6, v46
	ds_write_b32 v5, v0 offset:63488
	s_waitcnt vmcnt(0)
	v_mul_f32_e32 v6, 0xbfb8aa3b, v47
	v_exp_f32_e32 v6, v6
	s_nop 0
	v_add_f32_e32 v6, 1.0, v6
	v_div_scale_f32 v7, s[8:9], v6, v6, v47
	v_rcp_f32_e32 v8, v7
	v_div_scale_f32 v9, vcc, v47, v6, v47
	v_fma_f32 v10, -v7, v8, 1.0
	v_fmac_f32_e32 v8, v10, v8
	v_mul_f32_e32 v10, v9, v8
	v_fma_f32 v11, -v7, v10, v9
	v_fmac_f32_e32 v10, v11, v8
	v_fma_f32 v7, -v7, v10, v9
	v_div_fmas_f32 v7, v7, v8, v10
	v_div_fixup_f32 v0, v7, v6, v47
	ds_write_b32 v2, v0 offset:38912
